# speedup vs baseline: 1.0063x; 1.0063x over previous
; DEV void post_rows(const Params& p, const float* __restrict__ xsrc, const float* __restrict__ g, bool final) {
;     ...
;       for (int e = 0; e < 4; ++e) { xn[e] = xo[e] + mv[c * 8 + e] * rm * g0[e]; xn[4 + e] = xo[4 + e] + mv[c * 8 + 4 + e] * rm * g1[e]; }
;       if (final) { *reinterpret_cast<f32x4*>(p.out + (size_t)row * DM + idx) = (f32x4){xn[0], xn[1], xn[2], xn[3]};
;                    *reinterpret_cast<f32x4*>(p.out + (size_t)row * DM + idx + 4) = (f32x4){xn[4], xn[5], xn[6], xn[7]}; }
.LBB0_755:
	v_lshlrev_b64 v[54:55], 13, v[40:41]
	s_andn2_b64 vcc, exec, s[6:7]
	v_lshl_add_u64 v[54:55], s[56:57], 0, v[54:55]
	s_cbranch_vccnz .LBB0_757
	v_lshlrev_b32_e32 v192, 2, v42
	v_lshl_add_u64 v[86:87], v[54:55], 0, v[192:193]
	v_mov_b32_e32 v49, 0
	global_store_dwordx4 v[86:87], v[36:39], off nt
	global_store_dwordx4 v[86:87], v[32:35], off offset:16 nt

; DEV void post_rows(const Params& p, const float* __restrict__ xsrc, const float* __restrict__ g, bool final) {
;     ...
;       if (final) { *reinterpret_cast<f32x4*>(p.out + (size_t)row * DM + idx) = (f32x4){xn[0], xn[1], xn[2], xn[3]};
;                    *reinterpret_cast<f32x4*>(p.out + (size_t)row * DM + idx + 4) = (f32x4){xn[4], xn[5], xn[6], xn[7]}; }
.LBB0_759:
	s_andn2_b64 vcc, exec, s[0:1]
	s_cbranch_vccnz .LBB0_761
	v_lshlrev_b32_e32 v192, 2, v42
	v_lshl_add_u64 v[78:79], v[54:55], 0, v[192:193]
	v_mov_b32_e32 v57, v49
	global_store_dwordx4 v[78:79], v[36:39], off offset:2048 nt
	global_store_dwordx4 v[78:79], v[32:35], off offset:2064 nt

; DEV void post_rows(const Params& p, const float* __restrict__ xsrc, const float* __restrict__ g, bool final) {
;     ...
;       if (final) { *reinterpret_cast<f32x4*>(p.out + (size_t)row * DM + idx) = (f32x4){xn[0], xn[1], xn[2], xn[3]};
;                    *reinterpret_cast<f32x4*>(p.out + (size_t)row * DM + idx + 4) = (f32x4){xn[4], xn[5], xn[6], xn[7]}; }
.LBB0_763:
	s_andn2_b64 vcc, exec, s[0:1]
	s_cbranch_vccnz .LBB0_765
	v_mov_b32_e32 v49, v193
	v_lshl_add_u64 v[70:71], v[54:55], 0, v[48:49]
	v_mov_b32_e32 v49, v57
	global_store_dwordx4 v[70:71], v[36:39], off nt
	global_store_dwordx4 v[70:71], v[32:35], off offset:16 nt

; DEV void post_rows(const Params& p, const float* __restrict__ xsrc, const float* __restrict__ g, bool final) {
;     ...
;       if (final) { *reinterpret_cast<f32x4*>(p.out + (size_t)row * DM + idx) = (f32x4){xn[0], xn[1], xn[2], xn[3]};
;                    *reinterpret_cast<f32x4*>(p.out + (size_t)row * DM + idx + 4) = (f32x4){xn[4], xn[5], xn[6], xn[7]}; }
.LBB0_769:
	v_mov_b32_e32 v51, v193
	v_lshl_add_u64 v[52:53], v[54:55], 0, v[50:51]
	v_mov_b32_e32 v43, v49
	global_store_dwordx4 v[52:53], v[36:39], off nt
	global_store_dwordx4 v[52:53], v[32:35], off offset:16 nt
	s_and_b64 vcc, exec, s[6:7]
	s_cbranch_vccnz .LBB0_752
